# convT early-issue (next tile's loads before LDS staging) extended to the two FW3 conversion loops
# baseline (speedup 1.0000x reference)
.LBB0_1046:
	v_mov_b32_e32 v4, v196
	s_mov_b32 s0, s2
	v_mov_b32_e32 v0, v196
	s_lshl_b32 s0, s0, 1
	v_readfirstlane_b32 s1, v0
	s_ashr_i32 s1, s1, 8
	v_mov_b32_e32 v0, v196
	s_add_i32 s1, s1, s0
	s_mov_b32 s43, 0xb000
	v_readfirstlane_b32 s0, v0
	s_ashr_i32 s0, s0, 8
	s_sub_i32 s0, s1, s0
	s_cmp_gt_i32 s0, 63
	s_mov_b32 s44, 0x16000
	s_mov_b32 s45, 0x21000
	s_mov_b32 s46, 0x84000
	s_mov_b32 s47, 0x2c000
	s_mov_b32 s48, 0x37000
	s_mov_b32 s50, 0x4d000
	s_mov_b32 s51, 0x58000
	s_brev_b32 s55, 18
	s_cbranch_scc1 .LBB0_1051
	v_mov_b32_e32 v0, v196
	v_bfe_u32 v47, v4, 6, 2
	v_readfirstlane_b32 s1, v0
	s_ashr_i32 s1, s1, 8
	s_add_i32 s1, s1, s0
	s_min_i32 s1, s1, 63
	s_lshl_b32 s20, s1, 6
	s_ashr_i32 s21, s20, 31
	s_lshl_b64 s[20:21], s[20:21], 2
	s_add_u32 s20, s62, s20
	v_lshlrev_b32_e32 v0, 2, v4
	v_lshlrev_b32_e32 v6, 12, v47
	s_addc_u32 s21, s63, s21
	v_and_b32_e32 v0, 0xfc, v0
	s_waitcnt vmcnt(15)
	v_or_b32_e32 v10, 0x4000, v6
	s_waitcnt vmcnt(12)
	v_or_b32_e32 v14, 0x8000, v6
	s_waitcnt vmcnt(7)
	v_or_b32_e32 v20, 0xc000, v6
	v_or_b32_e32 v28, 0x14000, v6
	v_lshl_add_u64 v[2:3], s[20:21], 0, v[0:1]
	s_waitcnt vmcnt(1)
	v_lshlrev_b32_e32 v8, 14, v47
	v_mov_b32_e32 v9, v1
	v_lshlrev_b32_e32 v12, 2, v10
	v_mov_b32_e32 v13, v1
	s_waitcnt vmcnt(0)
	v_lshlrev_b32_e32 v16, 2, v14
	v_mov_b32_e32 v17, v1
	v_lshlrev_b32_e32 v22, 2, v20
	s_waitcnt lgkmcnt(4)
	v_mov_b32_e32 v23, v1
	v_or_b32_e32 v24, 0x10000, v6
	v_lshlrev_b32_e32 v30, 2, v28
	v_mov_b32_e32 v31, v1
	s_waitcnt lgkmcnt(0)
	v_or_b32_e32 v32, 0x18000, v6
	v_or_b32_e32 v36, 0x1c000, v6
	v_lshl_add_u64 v[8:9], v[2:3], 0, v[8:9]
	v_lshl_add_u64 v[12:13], v[2:3], 0, v[12:13]
	v_lshl_add_u64 v[16:17], v[2:3], 0, v[16:17]
	v_lshl_add_u64 v[22:23], v[2:3], 0, v[22:23]
	v_lshlrev_b32_e32 v26, 2, v24
	v_mov_b32_e32 v27, v1
	v_lshl_add_u64 v[30:31], v[2:3], 0, v[30:31]
	v_lshlrev_b32_e32 v34, 2, v32
	v_mov_b32_e32 v35, v1
	v_lshlrev_b32_e32 v42, 2, v36
	v_mov_b32_e32 v43, v1
	v_lshl_add_u64 v[26:27], v[2:3], 0, v[26:27]
	v_lshl_add_u64 v[34:35], v[2:3], 0, v[34:35]
	v_lshl_add_u64 v[42:43], v[2:3], 0, v[42:43]
	global_load_dword v7, v[8:9], off nt
	s_nop 0
	global_load_dword v9, v[12:13], off nt
	global_load_dword v11, v[16:17], off nt
	s_nop 0
	global_load_dword v13, v[22:23], off nt
	global_load_dword v15, v[26:27], off nt
	global_load_dword v17, v[30:31], off nt
	global_load_dword v19, v[34:35], off nt
	global_load_dword v21, v[42:43], off nt
	v_or_b32_e32 v22, 0x20000, v6
	v_or_b32_e32 v30, 0x24000, v6
	v_lshlrev_b32_e32 v26, 2, v22
	v_mov_b32_e32 v27, v1
	v_lshlrev_b32_e32 v34, 2, v30
	v_mov_b32_e32 v35, v1
	v_or_b32_e32 v46, 0x28000, v6
	v_or_b32_e32 v48, 0x2c000, v6
	v_or_b32_e32 v50, 0x30000, v6
	v_or_b32_e32 v54, 0x34000, v6
	v_or_b32_e32 v58, 0x38000, v6
	v_or_b32_e32 v62, 0x3c000, v6
	v_lshl_add_u64 v[26:27], v[2:3], 0, v[26:27]
	v_lshl_add_u64 v[34:35], v[2:3], 0, v[34:35]
	v_lshlrev_b32_e32 v42, 2, v46
	v_mov_b32_e32 v43, v1
	v_lshlrev_b32_e32 v44, 2, v48
	v_mov_b32_e32 v45, v1
	v_lshlrev_b32_e32 v52, 2, v50
	v_mov_b32_e32 v53, v1
	v_lshlrev_b32_e32 v56, 2, v54
	v_mov_b32_e32 v57, v1
	v_lshlrev_b32_e32 v60, 2, v58
	v_mov_b32_e32 v61, v1
	v_lshlrev_b32_e32 v64, 2, v62
	v_mov_b32_e32 v65, v1
	v_lshl_add_u64 v[42:43], v[2:3], 0, v[42:43]
	v_lshl_add_u64 v[44:45], v[2:3], 0, v[44:45]
	v_lshl_add_u64 v[52:53], v[2:3], 0, v[52:53]
	v_lshl_add_u64 v[56:57], v[2:3], 0, v[56:57]
	v_lshl_add_u64 v[60:61], v[2:3], 0, v[60:61]
	v_lshl_add_u64 v[2:3], v[2:3], 0, v[64:65]
	global_load_dword v23, v[26:27], off nt
	global_load_dword v25, v[34:35], off nt
	s_nop 0
	global_load_dword v27, v[42:43], off nt
	global_load_dword v29, v[44:45], off nt
	global_load_dword v31, v[52:53], off nt
	global_load_dword v33, v[56:57], off nt
	global_load_dword v35, v[60:61], off nt
	global_load_dword v37, v[2:3], off nt
	v_bfe_u32 v41, v4, 3, 5
	v_lshlrev_b32_e32 v4, 3, v4
	v_and_b32_e32 v8, 56, v4
	v_lshlrev_b32_e32 v4, 1, v8
	v_mul_u32_u24_e32 v8, 0x41, v8
	v_readlane_b32 s4, v253, 6
	v_lshlrev_b32_e32 v8, 2, v8
	v_lshlrev_b32_e32 v12, 2, v41
	v_mov_b32_e32 v5, v1
	v_readlane_b32 s6, v253, 8
	v_readlane_b32 s7, v253, 9
	v_add3_u32 v43, s33, v8, v12
	v_mul_u32_u24_e32 v8, 0x104, v47
	v_lshl_add_u64 v[2:3], s[62:63], 0, v[0:1]
	v_lshl_add_u64 v[4:5], s[6:7], 0, v[4:5]
	v_or_b32_e32 v42, 32, v41
	v_add3_u32 v44, s33, v8, v0
	v_lshlrev_b32_e32 v0, 2, v6
	v_lshlrev_b32_e32 v6, 2, v10
	v_lshlrev_b32_e32 v8, 2, v14
	v_lshlrev_b32_e32 v10, 2, v20
	v_lshlrev_b32_e32 v12, 2, v24
	v_lshlrev_b32_e32 v14, 2, v28
	v_lshlrev_b32_e32 v16, 2, v32
	v_lshlrev_b32_e32 v20, 2, v36
	v_lshlrev_b32_e32 v22, 2, v22
	v_lshlrev_b32_e32 v24, 2, v30
	v_lshlrev_b32_e32 v26, 2, v46
	v_lshlrev_b32_e32 v28, 2, v48
	v_lshlrev_b32_e32 v30, 2, v50
	v_lshlrev_b32_e32 v32, 2, v54
	v_lshlrev_b32_e32 v34, 2, v58
	v_lshlrev_b32_e32 v36, 2, v62
	v_readlane_b32 s5, v253, 7
	s_waitcnt vmcnt(0)
	s_branch .LBB0_1049

.LBB0_1049:
	v_mov_b32_e32 v45, v196
	s_mov_b32 s1, s34
	s_waitcnt vmcnt(2)
	v_mov_b32_e32 v80, v7
	v_mov_b32_e32 v81, v9
	v_mov_b32_e32 v82, v11
	v_mov_b32_e32 v83, v13
	v_mov_b32_e32 v84, v15
	v_mov_b32_e32 v85, v17
	v_mov_b32_e32 v86, v19
	v_mov_b32_e32 v87, v21
	v_mov_b32_e32 v88, v23
	v_mov_b32_e32 v89, v25
	v_mov_b32_e32 v90, v27
	v_mov_b32_e32 v91, v29
	v_mov_b32_e32 v92, v31
	v_mov_b32_e32 v93, v33
	v_mov_b32_e32 v94, v35
	v_mov_b32_e32 v95, v37
	s_lshl_b32 s1, s1, 1
	s_add_i32 s1, s1, s0
	s_cmp_gt_i32 s1, 63
	v_readfirstlane_b32 s1, v45
	s_cbranch_scc1 .Lcv20_nn
	s_mov_b32 s20, s34
	v_mov_b32_e32 v7, v196
	s_lshl_b32 s20, s20, 1
	s_add_i32 s20, s20, s0
	v_readfirstlane_b32 s21, v7
	s_ashr_i32 s21, s21, 8
	s_add_i32 s20, s20, s21
	s_min_i32 s20, s20, 63
	s_lshl_b32 s20, s20, 6
	s_ashr_i32 s21, s20, 31
	v_lshl_add_u64 v[46:47], s[20:21], 2, v[2:3]
	v_lshl_add_u64 v[48:49], v[46:47], 0, v[0:1]
	v_mov_b32_e32 v7, v1
	v_mov_b32_e32 v9, v1
	v_mov_b32_e32 v11, v1
	v_mov_b32_e32 v13, v1
	v_mov_b32_e32 v15, v1
	v_mov_b32_e32 v17, v1
	v_mov_b32_e32 v21, v1
	v_mov_b32_e32 v23, v1
	v_lshl_add_u64 v[50:51], v[46:47], 0, v[6:7]
	v_lshl_add_u64 v[52:53], v[46:47], 0, v[8:9]
	v_lshl_add_u64 v[54:55], v[46:47], 0, v[10:11]
	v_lshl_add_u64 v[56:57], v[46:47], 0, v[12:13]
	v_lshl_add_u64 v[58:59], v[46:47], 0, v[14:15]
	v_lshl_add_u64 v[60:61], v[46:47], 0, v[16:17]
	v_lshl_add_u64 v[62:63], v[46:47], 0, v[20:21]
	global_load_dword v7, v[48:49], off nt
	global_load_dword v9, v[50:51], off nt
	global_load_dword v11, v[52:53], off nt
	global_load_dword v13, v[54:55], off nt
	global_load_dword v15, v[56:57], off nt
	global_load_dword v17, v[58:59], off nt
	global_load_dword v19, v[60:61], off nt
	global_load_dword v21, v[62:63], off nt
	v_lshl_add_u64 v[48:49], v[46:47], 0, v[22:23]
	v_mov_b32_e32 v25, v1
	v_mov_b32_e32 v27, v1
	v_mov_b32_e32 v29, v1
	v_mov_b32_e32 v31, v1
	v_mov_b32_e32 v33, v1
	v_mov_b32_e32 v35, v1
	v_mov_b32_e32 v37, v1
	v_lshl_add_u64 v[50:51], v[46:47], 0, v[24:25]
	v_lshl_add_u64 v[52:53], v[46:47], 0, v[26:27]
	v_lshl_add_u64 v[54:55], v[46:47], 0, v[28:29]
	v_lshl_add_u64 v[56:57], v[46:47], 0, v[30:31]
	v_lshl_add_u64 v[58:59], v[46:47], 0, v[32:33]
	v_lshl_add_u64 v[60:61], v[46:47], 0, v[34:35]
	v_lshl_add_u64 v[46:47], v[46:47], 0, v[36:37]
	global_load_dword v23, v[48:49], off nt
	global_load_dword v25, v[50:51], off nt
	global_load_dword v27, v[52:53], off nt
	global_load_dword v29, v[54:55], off nt
	global_load_dword v31, v[56:57], off nt
	global_load_dword v33, v[58:59], off nt
	global_load_dword v35, v[60:61], off nt
	global_load_dword v37, v[46:47], off nt
.Lcv20_nn:
	ds_write_b32 v44, v80
	ds_write_b32 v44, v81 offset:1040
	ds_write_b32 v44, v82 offset:2080
	ds_write_b32 v44, v83 offset:3120
	ds_write_b32 v44, v84 offset:4160
	ds_write_b32 v44, v85 offset:5200
	ds_write_b32 v44, v86 offset:6240
	ds_write_b32 v44, v87 offset:7280
	ds_write_b32 v44, v88 offset:8320
	ds_write_b32 v44, v89 offset:9360
	ds_write_b32 v44, v90 offset:10400
	ds_write_b32 v44, v91 offset:11440
	ds_write_b32 v44, v92 offset:12480
	ds_write_b32 v44, v93 offset:13520
	ds_write_b32 v44, v94 offset:14560
	ds_write_b32 v44, v95 offset:15600
	s_waitcnt lgkmcnt(0)
	s_barrier
	s_branch .LBB0_1048
.LBB0_1051:
	v_mov_b32_e32 v4, v196
	s_mov_b32 s0, s2
	v_mov_b32_e32 v0, v196
	s_lshl_b32 s0, s0, 1
	v_readfirstlane_b32 s1, v0
	s_ashr_i32 s1, s1, 8
	v_mov_b32_e32 v0, v196
	s_add_i32 s1, s1, s0
	s_nop 0
	v_readfirstlane_b32 s0, v0
	s_ashr_i32 s0, s0, 8
	s_sub_i32 s0, s1, s0
	s_cmp_lt_i32 s0, 64
	s_cbranch_scc0 .LBB0_1056
	v_mov_b32_e32 v0, v196
	v_bfe_u32 v47, v4, 6, 2
	v_readfirstlane_b32 s1, v0
	s_ashr_i32 s1, s1, 8
	s_add_i32 s1, s1, s0
	s_min_i32 s1, s1, 63
	s_lshl_b32 s20, s1, 6
	s_ashr_i32 s21, s20, 31
	s_lshl_b64 s[20:21], s[20:21], 2
	v_readlane_b32 s4, v253, 12
	v_readlane_b32 s5, v253, 13
	s_add_u32 s20, s4, s20
	v_lshlrev_b32_e32 v0, 2, v4
	v_lshlrev_b32_e32 v6, 12, v47
	s_addc_u32 s21, s5, s21
	v_and_b32_e32 v0, 0xfc, v0
	s_waitcnt vmcnt(15)
	v_or_b32_e32 v10, 0x4000, v6
	s_waitcnt vmcnt(12)
	v_or_b32_e32 v14, 0x8000, v6
	s_waitcnt vmcnt(7)
	v_or_b32_e32 v20, 0xc000, v6
	v_or_b32_e32 v28, 0x14000, v6
	v_lshl_add_u64 v[2:3], s[20:21], 0, v[0:1]
	s_waitcnt vmcnt(1)
	v_lshlrev_b32_e32 v8, 14, v47
	v_mov_b32_e32 v9, v1
	v_lshlrev_b32_e32 v12, 2, v10
	v_mov_b32_e32 v13, v1
	s_waitcnt vmcnt(0)
	v_lshlrev_b32_e32 v16, 2, v14
	v_mov_b32_e32 v17, v1
	v_lshlrev_b32_e32 v22, 2, v20
	s_waitcnt lgkmcnt(4)
	v_mov_b32_e32 v23, v1
	v_or_b32_e32 v24, 0x10000, v6
	v_lshlrev_b32_e32 v30, 2, v28
	v_mov_b32_e32 v31, v1
	s_waitcnt lgkmcnt(0)
	v_or_b32_e32 v32, 0x18000, v6
	v_or_b32_e32 v36, 0x1c000, v6
	v_lshl_add_u64 v[8:9], v[2:3], 0, v[8:9]
	v_lshl_add_u64 v[12:13], v[2:3], 0, v[12:13]
	v_lshl_add_u64 v[16:17], v[2:3], 0, v[16:17]
	v_lshl_add_u64 v[22:23], v[2:3], 0, v[22:23]
	v_lshlrev_b32_e32 v26, 2, v24
	v_mov_b32_e32 v27, v1
	v_lshl_add_u64 v[30:31], v[2:3], 0, v[30:31]
	v_lshlrev_b32_e32 v34, 2, v32
	v_mov_b32_e32 v35, v1
	v_lshlrev_b32_e32 v42, 2, v36
	v_mov_b32_e32 v43, v1
	v_lshl_add_u64 v[26:27], v[2:3], 0, v[26:27]
	v_lshl_add_u64 v[34:35], v[2:3], 0, v[34:35]
	v_lshl_add_u64 v[42:43], v[2:3], 0, v[42:43]
	global_load_dword v7, v[8:9], off nt
	s_nop 0
	global_load_dword v9, v[12:13], off nt
	global_load_dword v11, v[16:17], off nt
	s_nop 0
	global_load_dword v13, v[22:23], off nt
	global_load_dword v15, v[26:27], off nt
	global_load_dword v17, v[30:31], off nt
	global_load_dword v19, v[34:35], off nt
	global_load_dword v21, v[42:43], off nt
	v_or_b32_e32 v22, 0x20000, v6
	v_or_b32_e32 v30, 0x24000, v6
	v_lshlrev_b32_e32 v26, 2, v22
	v_mov_b32_e32 v27, v1
	v_lshlrev_b32_e32 v34, 2, v30
	v_mov_b32_e32 v35, v1
	v_or_b32_e32 v46, 0x28000, v6
	v_or_b32_e32 v48, 0x2c000, v6
	v_or_b32_e32 v50, 0x30000, v6
	v_or_b32_e32 v54, 0x34000, v6
	v_or_b32_e32 v58, 0x38000, v6
	v_or_b32_e32 v62, 0x3c000, v6
	v_lshl_add_u64 v[26:27], v[2:3], 0, v[26:27]
	v_lshl_add_u64 v[34:35], v[2:3], 0, v[34:35]
	v_lshlrev_b32_e32 v42, 2, v46
	v_mov_b32_e32 v43, v1
	v_lshlrev_b32_e32 v44, 2, v48
	v_mov_b32_e32 v45, v1
	v_lshlrev_b32_e32 v52, 2, v50
	v_mov_b32_e32 v53, v1
	v_lshlrev_b32_e32 v56, 2, v54
	v_mov_b32_e32 v57, v1
	v_lshlrev_b32_e32 v60, 2, v58
	v_mov_b32_e32 v61, v1
	v_lshlrev_b32_e32 v64, 2, v62
	v_mov_b32_e32 v65, v1
	v_lshl_add_u64 v[42:43], v[2:3], 0, v[42:43]
	v_lshl_add_u64 v[44:45], v[2:3], 0, v[44:45]
	v_lshl_add_u64 v[52:53], v[2:3], 0, v[52:53]
	v_lshl_add_u64 v[56:57], v[2:3], 0, v[56:57]
	v_lshl_add_u64 v[60:61], v[2:3], 0, v[60:61]
	v_lshl_add_u64 v[2:3], v[2:3], 0, v[64:65]
	global_load_dword v23, v[26:27], off nt
	global_load_dword v25, v[34:35], off nt
	s_nop 0
	global_load_dword v27, v[42:43], off nt
	global_load_dword v29, v[44:45], off nt
	global_load_dword v31, v[52:53], off nt
	global_load_dword v33, v[56:57], off nt
	global_load_dword v35, v[60:61], off nt
	global_load_dword v37, v[2:3], off nt
	v_bfe_u32 v41, v4, 3, 5
	v_lshlrev_b32_e32 v4, 3, v4
	v_and_b32_e32 v8, 56, v4
	v_lshlrev_b32_e32 v4, 1, v8
	v_mul_u32_u24_e32 v8, 0x41, v8
	v_lshl_add_u64 v[2:3], s[4:5], 0, v[0:1]
	v_readlane_b32 s4, v253, 10
	v_lshlrev_b32_e32 v8, 2, v8
	v_lshlrev_b32_e32 v12, 2, v41
	v_mov_b32_e32 v5, v1
	v_readlane_b32 s5, v253, 11
	v_add3_u32 v43, s33, v8, v12
	v_mul_u32_u24_e32 v8, 0x104, v47
	v_lshl_add_u64 v[4:5], s[4:5], 0, v[4:5]
	v_or_b32_e32 v42, 32, v41
	v_add3_u32 v44, s33, v8, v0
	v_lshlrev_b32_e32 v0, 2, v6
	v_lshlrev_b32_e32 v6, 2, v10
	v_lshlrev_b32_e32 v8, 2, v14
	v_lshlrev_b32_e32 v10, 2, v20
	v_lshlrev_b32_e32 v12, 2, v24
	v_lshlrev_b32_e32 v14, 2, v28
	v_lshlrev_b32_e32 v16, 2, v32
	v_lshlrev_b32_e32 v20, 2, v36
	v_lshlrev_b32_e32 v22, 2, v22
	v_lshlrev_b32_e32 v24, 2, v30
	v_lshlrev_b32_e32 v26, 2, v46
	v_lshlrev_b32_e32 v28, 2, v48
	v_lshlrev_b32_e32 v30, 2, v50
	v_lshlrev_b32_e32 v32, 2, v54
	v_lshlrev_b32_e32 v34, 2, v58
	v_lshlrev_b32_e32 v36, 2, v62
	s_waitcnt vmcnt(0)
	s_branch .LBB0_1054
